# each phase start touches the next GEMM phase's weight matrix (one dword per 64 B via LDS-DMA into unused LDS) so it is in the memory-side cache when streamed
# speedup vs baseline: 1.0065x; 1.0065x over previous
; __global__ void __launch_bounds__(512, 2) mega_fwd(Args args) {
;     ...
;             const int q = ph - 1, c = q / PH_PER_CHUNK, r = q - c * PH_PER_CHUNK;
;             const bool is_prompt = c < 2;
;             float* X = args.out + (size_t)c * TC * D;
;             const int L = is_prompt ? 2048 : 8192;
;             bf16_t* xb = (bf16_t*)(ws + ((c & 1) ? WS_XB : WS_X16));
;             {
;                 const int l = r / 9, k = r - l * 9;
;                 const bf16_t* WL = Wb + (size_t)l * W_LAYER_ELEMS;
;                 if (k == 0 || k == 7) {
.LBB0_18:
	v_readfirstlane_b32 s24, v196
	s_lshr_b32 s1, s24, 6
	v_readlane_b32 s0, v254, 6
	s_mov_b32 s21, s20
	s_add_i32 s0, s0, s1
	v_and_b32_e32 v170, 63, v196
	v_writelane_b32 v255, s1, 42
	s_cmp_lg_u32 s21, 0
	s_mov_b64 s[8:9], -1
	s_cbranch_scc0 .LBB0_422
	s_add_i32 s1, s21, -1
	s_mul_hi_i32 s4, s1, 0x38e38e39
	s_lshr_b32 s5, s4, 31
	s_ashr_i32 s4, s4, 2
	s_add_i32 s30, s4, s5
	s_mul_i32 s4, s30, 0xffffffee
	s_add_i32 s5, s4, s1
	s_bitcmp0_b32 s30, 0
	s_mov_b32 s1, 0x1d800000
	s_cselect_b32 s1, s1, 0x9e00000
	s_add_u32 s76, s80, s1
	s_mul_hi_i32 s1, s5, 0x38e38e39
	s_addc_u32 s77, s81, 0
	s_lshr_b32 s4, s1, 31
	s_ashr_i32 s12, s1, 1
	s_add_i32 s12, s12, s4
	s_mul_i32 s1, s12, -9
	v_writelane_b32 v255, s5, 43
	s_add_i32 s1, s1, s5
	s_mul_i32 s5, s12, 0x3180000
	s_mul_hi_i32 s4, s12, 0x3180000
	s_add_u32 s5, s80, s5
	v_writelane_b32 v255, s5, 44
	s_addc_u32 s4, s81, s4
	v_writelane_b32 v255, s4, 45
	s_mov_b32 s8, 0
	s_mov_b32 s9, 0
	s_cmp_eq_u32 s1, 0
	s_cselect_b32 s8, 0x580000, s8
	s_cselect_b32 s9, 0xb00000, s9
	s_cmp_eq_u32 s1, 1
	s_cselect_b32 s8, 0xb80000, s8
	s_cselect_b32 s9, 0x1080000, s9
	s_cmp_eq_u32 s1, 4
	s_cselect_b32 s8, 0x300000, s8
	s_cselect_b32 s9, 0x1c00000, s9
	s_cmp_eq_u32 s1, 5
	s_cselect_b32 s8, 0x200000, s8
	s_cselect_b32 s9, 0x1f00000, s9
	s_cmp_eq_u32 s1, 6
	s_cselect_b32 s8, 0xb00000, s8
	s_cselect_b32 s9, 0x2100000, s9
	s_cmp_eq_u32 s1, 7
	s_cselect_b32 s8, 0x580000, s8
	s_cselect_b32 s9, 0x2c00000, s9
	s_cmp_eq_u32 s1, 8
	s_cselect_b32 s8, 0xb00000, s8
	s_cselect_b32 s9, 0x3180000, s9
	s_cmp_eq_u32 s8, 0
	s_cbranch_scc1 .Lwpf_skip
	s_mov_b32 s100, s5
	s_mov_b32 s101, s4
	s_cmp_eq_u32 s1, 8
	s_cselect_b32 s38, s12, 0
	s_cmp_eq_u32 s38, 1
	s_cselect_b32 s100, s80, s100
	s_cselect_b32 s101, s81, s101
	s_cselect_b32 s9, 0, s9
	v_lshl_add_u32 v1, s0, 6, v170
	v_lshlrev_b32_e32 v1, 6, v1
	s_add_i32 s38, s8, -64
	v_min_u32_e32 v0, s38, v1
	v_add_u32_e32 v0, s9, v0
	s_lshr_b32 s8, s24, 6
	s_lshl_b32 s8, s8, 9
	s_add_i32 m0, s8, 0x20000
	s_nop 0
	global_load_lds_dword v0, s[100:101]
	v_add_u32_e32 v1, 0x800000, v1
	v_min_u32_e32 v0, s38, v1
	v_add_u32_e32 v0, s9, v0
	s_add_i32 m0, s8, 0x20100
	s_nop 0
	global_load_lds_dword v0, s[100:101]
.Lwpf_skip:
	s_mov_b64 s[4:5], 0
	v_writelane_b32 v255, s4, 46
	s_mov_b64 s[38:39], -1
	s_mov_b64 s[8:9], 0
	s_cmp_lt_i32 s1, 4
	v_writelane_b32 v255, s5, 47
	s_mov_b64 s[64:65], 0
	s_mov_b64 s[66:67], 0
	s_cbranch_scc1 .LBB0_39
	s_cmp_gt_i32 s1, 6
	s_cbranch_scc0 .LBB0_23
	s_mov_b64 s[4:5], -1
	v_writelane_b32 v255, s4, 46
	s_mov_b64 s[38:39], 0
	s_cmp_gt_i32 s1, 7
	v_writelane_b32 v255, s5, 47
	s_cbranch_scc0 .LBB0_24
	s_mov_b64 s[4:5], 0
	v_writelane_b32 v255, s4, 46
	s_cmp_eq_u32 s1, 8
	s_mov_b64 s[64:65], -1
	v_writelane_b32 v255, s5, 47
	s_cselect_b64 s[66:67], -1, 0
	s_branch .LBB0_24

; __global__ void __launch_bounds__(512, 2) mega_fwd(Args args) {
	.amdhsa_kernel _Z8mega_fwd4Args
		.amdhsa_group_segment_fixed_size 0
		.amdhsa_private_segment_fixed_size 0
		.amdhsa_kernarg_size 424
		.amdhsa_user_sgpr_count 2
		.amdhsa_user_sgpr_dispatch_ptr 0
		.amdhsa_user_sgpr_queue_ptr 0
		.amdhsa_user_sgpr_kernarg_segment_ptr 1
		.amdhsa_user_sgpr_dispatch_id 0
		.amdhsa_user_sgpr_kernarg_preload_length 0
		.amdhsa_user_sgpr_kernarg_preload_offset 0
		.amdhsa_user_sgpr_private_segment_size 0
		.amdhsa_uses_dynamic_stack 0
		.amdhsa_enable_private_segment 0
		.amdhsa_system_sgpr_workgroup_id_x 1
		.amdhsa_system_sgpr_workgroup_id_y 0
		.amdhsa_system_sgpr_workgroup_id_z 0
		.amdhsa_system_sgpr_workgroup_info 0
		.amdhsa_system_vgpr_workitem_id 2
		.amdhsa_next_free_vgpr 256
		.amdhsa_next_free_sgpr 102
		.amdhsa_accum_offset 256
		.amdhsa_reserve_vcc 1
		.amdhsa_float_round_mode_32 0
		.amdhsa_float_round_mode_16_64 0
		.amdhsa_float_denorm_mode_32 3
		.amdhsa_float_denorm_mode_16_64 3
		.amdhsa_dx10_clamp 1
		.amdhsa_ieee_mode 1
		.amdhsa_fp16_overflow 0
		.amdhsa_tg_split 0
		.amdhsa_exception_fp_ieee_invalid_op 0
		.amdhsa_exception_fp_denorm_src 0
		.amdhsa_exception_fp_ieee_div_zero 0
		.amdhsa_exception_fp_ieee_overflow 0
		.amdhsa_exception_fp_ieee_underflow 0
		.amdhsa_exception_fp_ieee_inexact 0
		.amdhsa_exception_int_div_zero 0
	.end_amdhsa_kernel

; __global__ void __launch_bounds__(512, 2) mega_fwd(Args args) {
amdhsa.kernels:
  - .agpr_count:     0
    .args:
      - .offset:         0
        .size:           168
        .value_kind:     by_value
      - .offset:         168
        .size:           4
        .value_kind:     hidden_block_count_x
      - .offset:         172
        .size:           4
        .value_kind:     hidden_block_count_y
      - .offset:         176
        .size:           4
        .value_kind:     hidden_block_count_z
      - .offset:         180
        .size:           2
        .value_kind:     hidden_group_size_x
      - .offset:         182
        .size:           2
        .value_kind:     hidden_group_size_y
      - .offset:         184
        .size:           2
        .value_kind:     hidden_group_size_z
      - .offset:         186
        .size:           2
        .value_kind:     hidden_remainder_x
      - .offset:         188
        .size:           2
        .value_kind:     hidden_remainder_y
      - .offset:         190
        .size:           2
        .value_kind:     hidden_remainder_z
      - .offset:         208
        .size:           8
        .value_kind:     hidden_global_offset_x
      - .offset:         216
        .size:           8
        .value_kind:     hidden_global_offset_y
      - .offset:         224
        .size:           8
        .value_kind:     hidden_global_offset_z
      - .offset:         232
        .size:           2
        .value_kind:     hidden_grid_dims
      - .offset:         256
        .size:           8
        .value_kind:     hidden_multigrid_sync_arg
      - .offset:         288
        .size:           4
        .value_kind:     hidden_dynamic_lds_size
    .group_segment_fixed_size: 0
    .kernarg_segment_align: 8
    .kernarg_segment_size: 424
    .language:       OpenCL C
    .language_version:
      - 2
      - 0
    .max_flat_workgroup_size: 512
    .name:           _Z8mega_fwd4Args
    .private_segment_fixed_size: 0
    .sgpr_count:     108
    .sgpr_spill_count: 203
    .symbol:         _Z8mega_fwd4Args.kd
    .uniform_work_group_size: 1
    .uses_dynamic_stack: false
    .vgpr_count:     256
    .vgpr_spill_count: 0
    .wavefront_size: 64
